# grid barrier: release counter replicated per XCD (last arriver of each XCD adds to 16 copies, each WG polls its own XCD's copy: 32 pollers per address instead of 256)
# speedup vs baseline: 1.0088x; 1.0088x over previous
.LBB0_122:
	s_or_b64 exec, exec, s[10:11]
	v_cvt_f32_u32_e32 v4, v2
	s_waitcnt vmcnt(0)
	v_readfirstlane_b32 s2, v3
	v_sub_u32_e32 v3, 0, v2
	v_rcp_iflag_f32_e32 v4, v4
	v_add_u32_e32 v5, s2, v1
	v_mul_f32_e32 v4, 0x4f7ffffe, v4
	v_cvt_u32_f32_e32 v4, v4
	v_mul_lo_u32 v1, v3, v4
	v_mul_hi_u32 v1, v4, v1
	v_add_u32_e32 v1, v4, v1
	v_mul_hi_u32 v1, v5, v1
	v_mul_lo_u32 v3, v1, v2
	v_sub_u32_e32 v3, v5, v3
	v_add_u32_e32 v4, 1, v1
	v_cmp_ge_u32_e32 vcc, v3, v2
	s_nop 1
	v_cndmask_b32_e32 v1, v1, v4, vcc
	v_sub_u32_e32 v4, v3, v2
	v_cndmask_b32_e32 v3, v3, v4, vcc
	v_add_u32_e32 v4, 1, v1
	v_cmp_ge_u32_e32 vcc, v3, v2
	v_add_u32_e32 v3, 1, v5
	s_nop 0
	v_cndmask_b32_e32 v1, v1, v4, vcc
	v_mul_lo_u32 v4, v2, v1
	v_add_u32_e32 v2, v4, v2
	s_waitcnt lgkmcnt(0)
	v_add_u32_e32 v4, 1, v1
	v_mul_lo_u32 v4, v4, v0
	v_readlane_b32 s14, v252, 2
	v_readlane_b32 s15, v252, 3
	s_add_u32 s14, s14, 0x2400
	s_addc_u32 s15, s15, 0
	v_mov_b32_e32 v6, 0
	v_cmp_ne_u32_e32 vcc, v3, v2
	s_cbranch_vccnz .Lxb_wait_0
	buffer_wbl2 sc1
	s_waitcnt vmcnt(0)
	v_mov_b32_e32 v5, 1
	global_atomic_add v6, v5, s[14:15]
	global_atomic_add v6, v5, s[14:15] offset:256
	global_atomic_add v6, v5, s[14:15] offset:512
	global_atomic_add v6, v5, s[14:15] offset:768
	global_atomic_add v6, v5, s[14:15] offset:1024
	global_atomic_add v6, v5, s[14:15] offset:1280
	global_atomic_add v6, v5, s[14:15] offset:1536
	global_atomic_add v6, v5, s[14:15] offset:1792
	global_atomic_add v6, v5, s[14:15] offset:2048
	global_atomic_add v6, v5, s[14:15] offset:2304
	global_atomic_add v6, v5, s[14:15] offset:2560
	global_atomic_add v6, v5, s[14:15] offset:2816
	global_atomic_add v6, v5, s[14:15] offset:3072
	global_atomic_add v6, v5, s[14:15] offset:3328
	global_atomic_add v6, v5, s[14:15] offset:3584
	global_atomic_add v6, v5, s[14:15] offset:3840
.Lxb_wait_0:
	buffer_inv sc1
	v_readlane_b32 s16, v252, 4
	s_nop 3
	s_lshl_b32 s16, s16, 8
	s_add_u32 s14, s14, s16
	s_addc_u32 s15, s15, 0
	s_mov_b32 s16, 0
